# plus chunk-prep cumulative log decay by a DPP row scan and row broadcasts instead of six LDS permutes (both prep copies)
# speedup vs baseline: 1.0239x; 1.0004x over previous
; __device__ __forceinline__ void gdn_prep_item(LAS unsigned char* lds, int item, int b0, PrepRaw& R, int next_item, const bf16_t* qkv, const float* bg, const float* gconv_w, unsigned char* rec, float* gtarr) {
;     ...
;     if (wave == 0) {
;         float G = R.gi;
; #pragma unroll
;         for (int o = 1; o < 64; o <<= 1) { const float v = __shfl_up(G, o); if (lane >= o) G += v; }
;         const float Gl = __shfl(G, 63);
;         Gs[lane] = G; Bs[lane] = R.be; EG[lane] = __expf(G); DKs[lane] = __expf(Gl - G);
;         if (lane == 0) gtarr[item] = __expf(Gl);
;     }
.LBB0_477:
	s_waitcnt vmcnt(36)
	v_add_f32_dpp v37, v113, v113 row_shr:1 row_mask:0xf bank_mask:0xf bound_ctrl:1
	s_nop 1
	v_add_f32_dpp v37, v37, v37 row_shr:2 row_mask:0xf bank_mask:0xf bound_ctrl:1
	s_nop 1
	v_add_f32_dpp v37, v37, v37 row_shr:4 row_mask:0xf bank_mask:0xf bound_ctrl:1
	s_nop 1
	v_add_f32_dpp v37, v37, v37 row_shr:8 row_mask:0xf bank_mask:0xf bound_ctrl:1
	s_nop 1
	v_add_f32_dpp v37, v37, v37 row_bcast:15 row_mask:0xa bank_mask:0xf
	s_nop 1
	v_add_f32_dpp v37, v37, v37 row_bcast:31 row_mask:0xc bank_mask:0xf
	v_cmp_eq_u32_e32 vcc, 0, v118
	s_nop 0
	v_readlane_b32 s0, v37, 63
	v_lshl_add_u32 v66, v118, 2, 0
	v_add_u32_e32 v67, 0x1d000, v66
	v_add_u32_e32 v68, 0x1d200, v66
	v_mov_b32_e32 v36, s0
	ds_write_b32 v67, v37
	v_add_u32_e32 v67, 0x1d100, v66
	s_waitcnt vmcnt(35)
	ds_write_b32 v67, v35
	v_mul_f32_e32 v67, 0x3fb8aa3b, v37
	s_waitcnt lgkmcnt(2)
	v_sub_f32_e32 v37, v36, v37
	v_mul_f32_e32 v37, 0x3fb8aa3b, v37
	v_exp_f32_e32 v67, v67
	v_exp_f32_e32 v37, v37
	v_add_u32_e32 v66, 0x1d300, v66
	ds_write_b32 v68, v67
	ds_write_b32 v66, v37
	s_and_saveexec_b64 s[0:1], vcc
	s_cbranch_execz .LBB0_479
	v_mul_f32_e32 v36, 0x3fb8aa3b, v36
	v_exp_f32_e32 v36, v36
	s_lshl_b64 s[4:5], s[18:19], 2
	s_add_u32 s4, s58, s4
	s_addc_u32 s5, s57, s5
	global_store_dword v34, v36, s[4:5]

; __device__ __forceinline__ void gdn_prep_item(LAS unsigned char* lds, int item, int b0, PrepRaw& R, int next_item, const bf16_t* qkv, const float* bg, const float* gconv_w, unsigned char* rec, float* gtarr) {
;     ...
;     if (wave == 0) {
;         float G = R.gi;
; #pragma unroll
;         for (int o = 1; o < 64; o <<= 1) { const float v = __shfl_up(G, o); if (lane >= o) G += v; }
;         const float Gl = __shfl(G, 63);
;         Gs[lane] = G; Bs[lane] = R.be; EG[lane] = __expf(G); DKs[lane] = __expf(Gl - G);
;         if (lane == 0) gtarr[item] = __expf(Gl);
;     }
.LBB0_648:
	s_or_b64 exec, exec, s[0:1]
	s_ashr_i32 s19, s18, 31
	s_cmp_lg_u32 s20, 0
	v_and_b32_e32 v101, 63, v99
	s_cbranch_scc1 .LBB0_652
	s_waitcnt vmcnt(1)
	v_add_f32_dpp v63, v64, v64 row_shr:1 row_mask:0xf bank_mask:0xf bound_ctrl:1
	s_nop 1
	v_add_f32_dpp v63, v63, v63 row_shr:2 row_mask:0xf bank_mask:0xf bound_ctrl:1
	s_nop 1
	v_add_f32_dpp v63, v63, v63 row_shr:4 row_mask:0xf bank_mask:0xf bound_ctrl:1
	s_nop 1
	v_add_f32_dpp v63, v63, v63 row_shr:8 row_mask:0xf bank_mask:0xf bound_ctrl:1
	s_nop 1
	v_add_f32_dpp v63, v63, v63 row_bcast:15 row_mask:0xa bank_mask:0xf
	s_nop 1
	v_add_f32_dpp v63, v63, v63 row_bcast:31 row_mask:0xc bank_mask:0xf
	v_cmp_eq_u32_e32 vcc, 0, v101
	s_nop 0
	v_readlane_b32 s0, v63, 63
	s_nop 2
	v_mov_b32_e32 v62, s0
	v_lshl_add_u32 v64, v101, 2, 0
	v_add_u32_e32 v65, 0x1d000, v64
	ds_write_b32 v65, v63
	v_add_u32_e32 v65, 0x1d100, v64
	s_waitcnt vmcnt(0)
	ds_write_b32 v65, v58
	v_mul_f32_e32 v58, 0x3fb8aa3b, v63
	s_waitcnt lgkmcnt(2)
	v_sub_f32_e32 v63, v62, v63
	v_exp_f32_e32 v58, v58
	v_mul_f32_e32 v63, 0x3fb8aa3b, v63
	v_exp_f32_e32 v63, v63
	v_add_u32_e32 v65, 0x1d200, v64
	ds_write_b32 v65, v58
	v_add_u32_e32 v58, 0x1d300, v64
	ds_write_b32 v58, v63
	s_and_saveexec_b64 s[0:1], vcc
	s_cbranch_execz .LBB0_651
	v_mul_f32_e32 v58, 0x3fb8aa3b, v62
	v_exp_f32_e32 v58, v58
	s_lshl_b64 s[4:5], s[18:19], 2
	s_add_u32 s4, s58, s4
	s_addc_u32 s5, s57, s5
	v_mov_b32_e32 v62, 0
	global_store_dword v62, v58, s[4:5] sc0 sc1
